# P1 row loop: second-half shift/scale loads requested at the loop top with the first half's, counted waits renumbered
# baseline (speedup 1.0000x reference)
.LBB0_127:
	global_load_dwordx4 v[28:31], v[162:163], off
	s_waitcnt lgkmcnt(2)
	global_load_dwordx4 v[32:35], v[162:163], off offset:16
	global_load_dwordx4 v[20:23], v[162:163], off offset:2048
	global_load_dwordx4 v[24:27], v[162:163], off offset:2064
	s_ashr_i32 s4, s12, 12
	s_mul_hi_i32 s5, s4, 0x6000
	s_mulk_i32 s4, 0x6000
	s_add_u32 s44, s6, s4
	s_addc_u32 s45, s7, s5
	v_lshl_add_u64 v[166:167], s[44:45], 0, v[64:65]
	v_add_co_u32_e32 v168, vcc, s13, v166
	v_lshl_add_u64 v[172:173], v[166:167], 0, s[42:43]
	s_nop 0
	v_addc_co_u32_e32 v169, vcc, 0, v167, vcc
	s_waitcnt lgkmcnt(0)
	global_load_dwordx4 v[168:171], v[168:169], off
	s_nop 0
	global_load_dwordx4 v[184:187], v[172:173], off offset:16
	global_load_dwordx4 v[188:191], v64, s[44:45]
	global_load_dwordx4 v[226:229], v[172:173], off offset:2048
	global_load_dwordx4 v[230:233], v[172:173], off offset:2064
	global_load_dwordx4 v[234:237], v64, s[44:45] offset:2048
	global_load_dwordx4 v[244:247], v64, s[44:45] offset:2064
	s_waitcnt vmcnt(10)
	v_pk_mul_f32 v[166:167], v[30:31], v[30:31]
	v_pk_mul_f32 v[192:193], v[28:29], v[28:29]
	s_waitcnt vmcnt(9)
	v_pk_mul_f32 v[194:195], v[34:35], v[34:35]
	v_pk_mul_f32 v[196:197], v[32:33], v[32:33]
	v_pk_mov_b32 v[202:203], v[192:193], v[166:167] op_sel:[1,0]
	v_mov_b32_e32 v193, v167
	v_pk_mov_b32 v[166:167], v[196:197], v[194:195] op_sel:[1,0]
	v_mov_b32_e32 v197, v195
	s_waitcnt vmcnt(8)
	v_mul_f32_e32 v198, v21, v21
	v_mul_f32_e32 v200, v23, v23
	s_waitcnt vmcnt(7)
	v_mul_f32_e32 v201, v27, v27
	v_pk_add_f32 v[192:193], v[202:203], v[192:193]
	v_pk_add_f32 v[166:167], v[166:167], v[196:197]
	v_mul_f32_e32 v183, v26, v26
	v_mul_f32_e32 v204, v24, v24
	v_mul_f32_e32 v205, v25, v25
	v_pk_fma_f32 v[194:195], v[20:21], v[20:21], v[198:199] op_sel_hi:[1,1,0]
	v_pk_fma_f32 v[198:199], v[22:23], v[22:23], v[200:201] op_sel_hi:[1,1,0]
	v_pk_add_f32 v[192:193], v[192:193], v[192:193] op_sel:[0,1] op_sel_hi:[1,0]
	v_pk_add_f32 v[166:167], v[166:167], v[166:167] op_sel:[0,1] op_sel_hi:[1,0]
	v_mov_b32_e32 v195, v183
	v_mov_b32_e32 v199, v201
	v_mov_b32_e32 v193, v204
	v_mov_b32_e32 v167, v205
	v_pk_add_f32 v[194:195], v[194:195], v[198:199]
	v_pk_add_f32 v[166:167], v[192:193], v[166:167]
	s_waitcnt vmcnt(6)
	v_pk_add_f32 v[170:171], v[170:171], 1.0 op_sel_hi:[1,0]
	v_pk_add_f32 v[166:167], v[166:167], v[194:195]
	global_load_dwordx4 v[192:195], v64, s[44:45] offset:16
	v_add_f32_e32 v166, v166, v167
	ds_bpermute_b32 v167, v174, v166
	s_waitcnt vmcnt(6)
	v_pk_add_f32 v[186:187], v[186:187], 1.0 op_sel_hi:[1,0]
	v_pk_add_f32 v[184:185], v[184:185], 1.0 op_sel_hi:[1,0]
	s_waitcnt lgkmcnt(0)
	v_add_f32_e32 v166, v166, v167
	ds_bpermute_b32 v167, v175, v166
	s_waitcnt lgkmcnt(0)
	v_add_f32_e32 v166, v166, v167
	ds_bpermute_b32 v167, v176, v166
	s_waitcnt lgkmcnt(0)
	v_add_f32_e32 v166, v166, v167
	ds_bpermute_b32 v167, v177, v166
	s_waitcnt lgkmcnt(0)
	v_add_f32_e32 v183, v166, v167
	ds_bpermute_b32 v196, v178, v183
	v_lshl_add_u64 v[166:167], s[54:55], 0, v[164:165]
	v_add_co_u32_e32 v166, vcc, s14, v166
	s_waitcnt lgkmcnt(0)
	v_add_f32_e32 v183, v183, v196
	ds_bpermute_b32 v196, v179, v183
	v_addc_co_u32_e32 v167, vcc, 0, v167, vcc
	s_waitcnt lgkmcnt(0)
	v_add_f32_e32 v183, v183, v196
	v_fmamk_f32 v183, v183, 0x3a800000, v180
	v_mul_f32_e32 v196, 0x4f800000, v183
	v_cmp_gt_f32_e32 vcc, s3, v183
	s_nop 1
	v_cndmask_b32_e32 v183, v183, v196, vcc
	v_sqrt_f32_e32 v198, v183
	v_pk_add_f32 v[196:197], v[168:169], 1.0 op_sel_hi:[1,0]
	v_add_u32_e32 v168, -1, v198
	v_add_u32_e32 v169, 1, v198
	v_fma_f32 v199, -v168, v198, v183
	v_fma_f32 v200, -v169, v198, v183
	v_cmp_ge_f32_e64 s[4:5], 0, v199
	s_nop 1
	v_cndmask_b32_e64 v168, v198, v168, s[4:5]
	v_cmp_lt_f32_e64 s[4:5], 0, v200
	s_nop 1
	v_cndmask_b32_e64 v168, v168, v169, s[4:5]
	v_mul_f32_e32 v169, 0x37800000, v168
	v_cndmask_b32_e32 v168, v168, v169, vcc
	v_cmp_class_f32_e32 vcc, v183, v181
	s_nop 1
	v_cndmask_b32_e32 v168, v168, v183, vcc
	v_div_scale_f32 v169, s[4:5], v168, v168, 1.0
	v_rcp_f32_e32 v183, v169
	v_div_scale_f32 v198, vcc, 1.0, v168, 1.0
	v_fma_f32 v199, -v169, v183, 1.0
	v_fmac_f32_e32 v183, v199, v183
	v_mul_f32_e32 v199, v198, v183
	v_fma_f32 v200, -v169, v199, v198
	v_fmac_f32_e32 v199, v200, v183
	v_fma_f32 v169, -v169, v199, v198
	v_div_fmas_f32 v169, v169, v183, v199
	v_div_fixup_f32 v198, v169, v168, 1.0
	v_pk_mul_f32 v[30:31], v[30:31], v[198:199] op_sel_hi:[1,0]
	v_pk_mul_f32 v[28:29], v[28:29], v[198:199] op_sel_hi:[1,0]
	v_pk_mul_f32 v[34:35], v[34:35], v[198:199] op_sel_hi:[1,0]
	v_pk_mul_f32 v[32:33], v[32:33], v[198:199] op_sel_hi:[1,0]
	v_pk_mul_f32 v[30:31], v[6:7], v[30:31]
	v_pk_mul_f32 v[28:29], v[4:5], v[28:29]
	v_pk_mul_f32 v[34:35], v[2:3], v[34:35]
	v_pk_mul_f32 v[200:201], v[0:1], v[32:33]
	s_waitcnt vmcnt(5)
	v_pk_fma_f32 v[168:169], v[170:171], v[30:31], v[190:191]
	v_pk_fma_f32 v[170:171], v[196:197], v[28:29], v[188:189]
	s_waitcnt vmcnt(0)
	v_pk_fma_f32 v[32:33], v[186:187], v[34:35], v[194:195]
	v_pk_fma_f32 v[34:35], v[184:185], v[200:201], v[192:193]
	v_cvt_pk_bf16_f32 v28, v170, v171
	v_cvt_pk_bf16_f32 v29, v168, v169
	v_cvt_pk_bf16_f32 v30, v34, v35
	v_cvt_pk_bf16_f32 v31, v32, v33
	global_store_dwordx4 v[166:167], v[28:31], off
	s_nop 0
	s_nop 0
	s_nop 0
	s_nop 0
	s_nop 0
	v_pk_mul_f32 v[20:21], v[20:21], v[198:199] op_sel_hi:[1,0]
	v_pk_mul_f32 v[26:27], v[26:27], v[198:199] op_sel_hi:[1,0]
	v_pk_mul_f32 v[22:23], v[22:23], v[198:199] op_sel_hi:[1,0]
	v_pk_mul_f32 v[24:25], v[24:25], v[198:199] op_sel_hi:[1,0]
	v_pk_mul_f32 v[172:173], v[12:13], v[20:21]
	v_pk_mul_f32 v[196:197], v[10:11], v[26:27]
	v_pk_mul_f32 v[20:21], v[156:157], v[170:171]
	v_pk_mul_f32 v[26:27], v[144:145], v[170:171]
	v_pk_mul_f32 v[198:199], v[122:123], v[170:171]
	v_pk_mul_f32 v[200:201], v[110:111], v[170:171]
	v_pk_mul_f32 v[202:203], v[154:155], v[168:169]
	v_pk_mul_f32 v[204:205], v[138:139], v[168:169]
	v_pk_mul_f32 v[206:207], v[42:43], v[168:169]
	v_pk_mul_f32 v[208:209], v[108:109], v[168:169]
	v_pk_mul_f32 v[210:211], v[34:35], v[152:153] op_sel:[1,0]
	v_pk_mul_f32 v[212:213], v[34:35], v[54:55]
	v_pk_mul_f32 v[214:215], v[34:35], v[118:119]
	v_pk_mul_f32 v[218:219], v[32:33], v[150:151] op_sel:[1,0]
	v_pk_mul_f32 v[220:221], v[32:33], v[52:53]
	v_pk_fma_f32 v[20:21], v[158:159], v[170:171], v[20:21] op_sel:[0,1,0] op_sel_hi:[1,0,1]
	v_pk_fma_f32 v[26:27], v[146:147], v[170:171], v[26:27] op_sel:[0,1,0] op_sel_hi:[1,0,1]
	v_pk_fma_f32 v[198:199], v[124:125], v[170:171], v[198:199] op_sel:[0,1,0] op_sel_hi:[1,0,1]
	v_pk_fma_f32 v[170:171], v[60:61], v[170:171], v[200:201] op_sel:[0,1,0] op_sel_hi:[1,0,1]
	v_pk_fma_f32 v[200:201], v[160:161], v[168:169], v[202:203] op_sel:[0,1,0] op_sel_hi:[1,0,1]
	v_pk_fma_f32 v[202:203], v[148:149], v[168:169], v[204:205] op_sel:[0,1,0] op_sel_hi:[1,0,1]
	v_pk_mul_f32 v[216:217], v[34:35], v[36:37]
	v_pk_mul_f32 v[222:223], v[32:33], v[116:117]
	v_pk_mul_f32 v[224:225], v[32:33], v[120:121]
	v_pk_fma_f32 v[204:205], v[126:127], v[168:169], v[206:207] op_sel:[0,1,0] op_sel_hi:[1,0,1]
	v_pk_fma_f32 v[168:169], v[62:63], v[168:169], v[208:209] op_sel:[0,1,0] op_sel_hi:[1,0,1]
	v_pk_fma_f32 v[206:207], v[34:35], v[16:17], v[210:211] op_sel_hi:[0,1,1]
	v_pk_fma_f32 v[208:209], v[34:35], v[132:133], v[212:213] op_sel:[1,0,0] op_sel_hi:[0,1,1]
	v_pk_fma_f32 v[210:211], v[34:35], v[44:45], v[214:215] op_sel:[1,0,0] op_sel_hi:[0,1,1]
	v_pk_fma_f32 v[212:213], v[32:33], v[18:19], v[218:219] op_sel_hi:[0,1,1]
	v_pk_fma_f32 v[214:215], v[32:33], v[134:135], v[220:221] op_sel:[1,0,0] op_sel_hi:[0,1,1]
	v_pk_add_f32 v[20:21], v[20:21], v[200:201]
	v_pk_add_f32 v[26:27], v[26:27], v[202:203]
	v_pk_fma_f32 v[34:35], v[34:35], v[38:39], v[216:217] op_sel:[1,0,0] op_sel_hi:[0,1,1]
	v_pk_fma_f32 v[216:217], v[32:33], v[46:47], v[222:223] op_sel:[1,0,0] op_sel_hi:[0,1,1]
	v_pk_fma_f32 v[32:33], v[32:33], v[40:41], v[224:225] op_sel:[1,0,0] op_sel_hi:[0,1,1]
	v_pk_add_f32 v[200:201], v[206:207], v[212:213]
	v_pk_add_f32 v[202:203], v[208:209], v[214:215]
	v_pk_add_f32 v[198:199], v[198:199], v[204:205]
	v_pk_add_f32 v[20:21], v[20:21], 0 op_sel_hi:[1,0]
	v_pk_add_f32 v[26:27], v[26:27], 0 op_sel_hi:[1,0]
	v_pk_mul_f32 v[22:23], v[14:15], v[22:23]
	v_pk_add_f32 v[168:169], v[170:171], v[168:169]
	v_pk_add_f32 v[32:33], v[34:35], v[32:33]
	v_pk_add_f32 v[34:35], v[198:199], 0 op_sel_hi:[1,0]
	v_pk_add_f32 v[170:171], v[200:201], v[20:21]
	v_pk_add_f32 v[198:199], v[26:27], v[202:203]
	v_pk_mul_f32 v[24:25], v[8:9], v[24:25]
	v_pk_add_f32 v[168:169], v[168:169], 0 op_sel_hi:[1,0]
	v_pk_add_f32 v[204:205], v[210:211], v[216:217]
	v_pk_add_f32 v[32:33], v[168:169], v[32:33]
	v_pk_add_f32 v[34:35], v[34:35], v[204:205]
	s_nop 0
	v_pk_add_f32 v[20:21], v[228:229], 1.0 op_sel_hi:[1,0]
	v_pk_add_f32 v[26:27], v[226:227], 1.0 op_sel_hi:[1,0]
	s_nop 0
	v_pk_add_f32 v[28:29], v[232:233], 1.0 op_sel_hi:[1,0]
	v_pk_add_f32 v[30:31], v[230:231], 1.0 op_sel_hi:[1,0]
	s_nop 0
	v_pk_fma_f32 v[20:21], v[22:23], v[20:21], v[236:237]
	v_pk_fma_f32 v[26:27], v[172:173], v[26:27], v[234:235]
	s_nop 0
	v_pk_fma_f32 v[22:23], v[196:197], v[28:29], v[246:247]
	v_pk_fma_f32 v[24:25], v[24:25], v[30:31], v[244:245]
	v_pk_mul_f32 v[28:29], v[26:27], v[68:69]
	v_pk_mul_f32 v[168:169], v[26:27], v[66:67]
	v_pk_mul_f32 v[184:185], v[20:21], v[70:71]
	v_pk_mul_f32 v[188:189], v[20:21], v[100:101]
	v_pk_mul_f32 v[30:31], v[26:27], v[84:85]
	v_pk_mul_f32 v[186:187], v[20:21], v[86:87]
	v_pk_mul_f32 v[192:193], v[24:25], v[76:77]
	v_pk_mul_f32 v[194:195], v[22:23], v[78:79]
	v_pk_mul_f32 v[202:203], v[24:25], v[102:103]
	v_pk_mul_f32 v[204:205], v[22:23], v[112:113]
	v_pk_fma_f32 v[28:29], v[26:27], v[72:73], v[28:29] op_sel:[1,0,0] op_sel_hi:[0,1,1]
	v_pk_fma_f32 v[168:169], v[26:27], v[104:105], v[168:169] op_sel:[1,0,0] op_sel_hi:[0,1,1]
	v_pk_fma_f32 v[184:185], v[20:21], v[74:75], v[184:185] op_sel:[1,0,0] op_sel_hi:[0,1,1]
	v_pk_fma_f32 v[188:189], v[20:21], v[106:107], v[188:189] op_sel:[1,0,0] op_sel_hi:[0,1,1]
	v_pk_mul_f32 v[172:173], v[26:27], v[56:57]
	v_pk_mul_f32 v[190:191], v[20:21], v[128:129]
	v_pk_mul_f32 v[196:197], v[24:25], v[92:93]
	v_pk_mul_f32 v[200:201], v[22:23], v[94:95]
	v_pk_fma_f32 v[30:31], v[26:27], v[88:89], v[30:31] op_sel:[1,0,0] op_sel_hi:[0,1,1]
	v_pk_fma_f32 v[186:187], v[20:21], v[90:91], v[186:187] op_sel:[1,0,0] op_sel_hi:[0,1,1]
	v_pk_fma_f32 v[192:193], v[24:25], v[80:81], v[192:193] op_sel:[1,0,0] op_sel_hi:[0,1,1]
	v_pk_fma_f32 v[194:195], v[22:23], v[82:83], v[194:195] op_sel:[1,0,0] op_sel_hi:[0,1,1]
	v_pk_fma_f32 v[202:203], v[24:25], v[58:59], v[202:203] op_sel:[1,0,0] op_sel_hi:[0,1,1]
	v_pk_fma_f32 v[204:205], v[22:23], v[114:115], v[204:205] op_sel:[1,0,0] op_sel_hi:[0,1,1]
	v_pk_add_f32 v[28:29], v[28:29], v[184:185]
	v_pk_add_f32 v[168:169], v[168:169], v[188:189]
	v_pk_fma_f32 v[172:173], v[26:27], v[48:49], v[172:173] op_sel:[1,0,0] op_sel_hi:[0,1,1]
	v_pk_fma_f32 v[190:191], v[20:21], v[50:51], v[190:191] op_sel:[1,0,0] op_sel_hi:[0,1,1]
	v_pk_fma_f32 v[196:197], v[24:25], v[96:97], v[196:197] op_sel:[1,0,0] op_sel_hi:[0,1,1]
	v_pk_fma_f32 v[200:201], v[22:23], v[98:99], v[200:201] op_sel:[1,0,0] op_sel_hi:[0,1,1]
	v_pk_add_f32 v[184:185], v[192:193], v[194:195]
	v_pk_add_f32 v[30:31], v[30:31], v[186:187]
	v_pk_add_f32 v[188:189], v[202:203], v[204:205]
	v_pk_add_f32 v[28:29], v[170:171], v[28:29]
	v_pk_add_f32 v[34:35], v[34:35], v[168:169]
	v_pk_add_f32 v[186:187], v[196:197], v[200:201]
	v_pk_add_f32 v[172:173], v[172:173], v[190:191]
	v_pk_add_f32 v[30:31], v[198:199], v[30:31]
	v_pk_add_f32 v[28:29], v[28:29], v[184:185]
	v_pk_add_f32 v[34:35], v[34:35], v[188:189]
	v_pk_add_f32 v[32:33], v[32:33], v[172:173]
	v_pk_add_f32 v[30:31], v[30:31], v[186:187]
	ds_bpermute_b32 v168, v174, v28
	ds_bpermute_b32 v169, v174, v29
	ds_bpermute_b32 v172, v174, v34
	ds_bpermute_b32 v173, v174, v35
	v_pk_mul_f32 v[206:207], v[24:25], v[130:131]
	v_pk_mul_f32 v[208:209], v[22:23], v[136:137]
	ds_bpermute_b32 v170, v174, v30
	ds_bpermute_b32 v171, v174, v31
	v_pk_fma_f32 v[206:207], v[24:25], v[140:141], v[206:207] op_sel:[1,0,0] op_sel_hi:[0,1,1]
	v_pk_fma_f32 v[208:209], v[22:23], v[142:143], v[208:209] op_sel:[1,0,0] op_sel_hi:[0,1,1]
	v_pk_add_f32 v[190:191], v[206:207], v[208:209]
	s_waitcnt lgkmcnt(4)
	v_pk_add_f32 v[28:29], v[28:29], v[168:169]
	v_pk_add_f32 v[32:33], v[32:33], v[190:191]
	ds_bpermute_b32 v184, v174, v32
	ds_bpermute_b32 v185, v174, v33
	s_waitcnt lgkmcnt(4)
	v_pk_add_f32 v[34:35], v[34:35], v[172:173]
	s_waitcnt lgkmcnt(2)
	v_pk_add_f32 v[30:31], v[30:31], v[170:171]
	ds_bpermute_b32 v168, v175, v28
	ds_bpermute_b32 v169, v175, v29
	ds_bpermute_b32 v172, v175, v34
	ds_bpermute_b32 v173, v175, v35
	ds_bpermute_b32 v170, v175, v30
	ds_bpermute_b32 v171, v175, v31
	s_waitcnt lgkmcnt(6)
	v_pk_add_f32 v[32:33], v[32:33], v[184:185]
	s_waitcnt lgkmcnt(4)
	v_pk_add_f32 v[28:29], v[28:29], v[168:169]
	s_waitcnt lgkmcnt(2)
	v_pk_add_f32 v[34:35], v[34:35], v[172:173]
	ds_bpermute_b32 v184, v175, v32
	ds_bpermute_b32 v185, v175, v33
	s_waitcnt lgkmcnt(2)
	v_pk_add_f32 v[30:31], v[30:31], v[170:171]
	ds_bpermute_b32 v168, v176, v28
	ds_bpermute_b32 v169, v176, v29
	ds_bpermute_b32 v172, v176, v34
	ds_bpermute_b32 v173, v176, v35
	ds_bpermute_b32 v170, v176, v30
	ds_bpermute_b32 v171, v176, v31
	s_waitcnt lgkmcnt(6)
	v_pk_add_f32 v[32:33], v[32:33], v[184:185]
	s_waitcnt lgkmcnt(4)
	v_pk_add_f32 v[28:29], v[28:29], v[168:169]
	s_waitcnt lgkmcnt(2)
	v_pk_add_f32 v[34:35], v[34:35], v[172:173]
	ds_bpermute_b32 v172, v176, v32
	ds_bpermute_b32 v173, v176, v33
	ds_bpermute_b32 v168, v177, v28
	ds_bpermute_b32 v169, v177, v29
	s_waitcnt lgkmcnt(4)
	v_pk_add_f32 v[30:31], v[30:31], v[170:171]
	ds_bpermute_b32 v170, v177, v34
	ds_bpermute_b32 v171, v177, v35
	s_waitcnt lgkmcnt(4)
	v_pk_add_f32 v[32:33], v[32:33], v[172:173]
	s_waitcnt lgkmcnt(2)
	v_pk_add_f32 v[28:29], v[28:29], v[168:169]
	ds_bpermute_b32 v168, v177, v30
	ds_bpermute_b32 v169, v177, v31
	s_waitcnt lgkmcnt(2)
	v_pk_add_f32 v[34:35], v[34:35], v[170:171]
	ds_bpermute_b32 v170, v177, v32
	ds_bpermute_b32 v171, v177, v33
	ds_bpermute_b32 v186, v178, v34
	s_waitcnt lgkmcnt(3)
	v_pk_add_f32 v[30:31], v[30:31], v[168:169]
	ds_bpermute_b32 v168, v178, v28
	ds_bpermute_b32 v169, v178, v29
	s_waitcnt lgkmcnt(3)
	v_pk_add_f32 v[170:171], v[32:33], v[170:171]
	ds_bpermute_b32 v172, v178, v30
	ds_bpermute_b32 v173, v178, v31
	ds_bpermute_b32 v187, v178, v35
	ds_bpermute_b32 v188, v178, v170
	ds_bpermute_b32 v189, v178, v171
	v_cvt_pk_bf16_f32 v184, v26, v27
	s_waitcnt lgkmcnt(5)
	v_pk_add_f32 v[28:29], v[28:29], v[168:169]
	s_waitcnt lgkmcnt(3)
	v_pk_add_f32 v[32:33], v[30:31], v[172:173]
	s_waitcnt lgkmcnt(2)
	v_pk_add_f32 v[26:27], v[34:35], v[186:187]
	s_waitcnt lgkmcnt(0)
	v_pk_add_f32 v[30:31], v[170:171], v[188:189]
	ds_bpermute_b32 v168, v179, v28
	ds_bpermute_b32 v169, v179, v29
	ds_bpermute_b32 v172, v179, v32
	ds_bpermute_b32 v173, v179, v33
	ds_bpermute_b32 v34, v179, v26
	ds_bpermute_b32 v35, v179, v27
	ds_bpermute_b32 v170, v179, v30
	ds_bpermute_b32 v171, v179, v31
	v_cvt_pk_bf16_f32 v185, v20, v21
	v_cvt_pk_bf16_f32 v186, v24, v25
	v_cvt_pk_bf16_f32 v187, v22, v23
	global_store_dwordx4 v[166:167], v[184:187], off offset:1024
	s_and_saveexec_b64 s[4:5], s[0:1]
	s_cbranch_execz .LBB0_126
	s_add_u32 s44, s54, s28
	s_waitcnt lgkmcnt(4)
	v_pk_add_f32 v[22:23], v[32:33], v[172:173]
	v_pk_add_f32 v[20:21], v[28:29], v[168:169]
	s_addc_u32 s45, s55, s29
	s_waitcnt lgkmcnt(0)
	v_pk_add_f32 v[28:29], v[30:31], v[170:171]
	v_pk_add_f32 v[26:27], v[26:27], v[34:35]
	global_store_dwordx4 v182, v[20:23], s[44:45]
	global_store_dwordx4 v182, v[26:29], s[44:45] offset:16
	s_branch .LBB0_126
